# snakeB + the two P6 MFMA blocks with a register-rotated accumulator reordered too (pair-adjacent, rotated accumulators kept last in original order)
# speedup vs baseline: 1.0011x; 1.0011x over previous
.LBB0_1009:
	v_add_u32_e32 v0, s64, v187
	ds_read_b128 v[130:133], v0
	ds_read_b128 v[134:137], v0 offset:1024
	ds_read_b128 v[138:141], v0 offset:2048
	ds_read_b128 v[142:145], v0 offset:3072
	v_add_u32_e32 v0, s65, v187
	ds_read_b128 v[146:149], v0
	ds_read_b128 v[150:153], v0 offset:1024
	ds_read_b128 v[178:181], v0 offset:2048
	ds_read_b128 v[182:185], v0 offset:3072
	s_add_i32 s35, s42, 2
	s_add_u32 s43, s36, 0x3fc000
	s_addc_u32 s44, s37, 0
	s_cmp_eq_u32 s61, s42
	s_cselect_b32 s46, s28, s43
	s_cselect_b32 s47, s29, s44
	s_cselect_b32 s44, s30, s11
	s_cselect_b32 s45, s31, s27
	s_add_u32 s42, s46, 0x400000
	s_addc_u32 s43, s47, 0
	v_lshl_add_u64 v[0:1], s[36:37], 0, v[168:169]
	s_add_i32 m0, s51, 0xc000
	ds_read_b128 v[220:223], v215
	ds_read_b128 v[224:227], v215 offset:1024
	ds_read_b128 v[228:231], v215 offset:2048
	ds_read_b128 v[232:235], v215 offset:3072
	ds_read_b128 v[236:239], v215 offset:4096
	ds_read_b128 v[240:243], v215 offset:5120
	ds_read_b128 v[244:247], v215 offset:6144
	ds_read_b128 v[248:251], v215 offset:7168
	global_load_lds_dwordx4 v[0:1], off
	v_lshl_add_u64 v[0:1], s[36:37], 0, v[170:171]
	s_add_i32 m0, s51, 0xe000
	s_nop 0
	global_load_lds_dwordx4 v[0:1], off
	s_waitcnt vmcnt(8)
	s_waitcnt lgkmcnt(0)
	s_barrier
	v_mfma_f32_16x16x32_bf16 v[114:117], v[130:133], v[220:223], v[114:117]
	v_mfma_f32_16x16x32_bf16 v[114:117], v[134:137], v[224:227], v[114:117]
	v_mfma_f32_16x16x32_bf16 v[110:113], v[134:137], v[232:235], v[110:113]
	v_mfma_f32_16x16x32_bf16 v[110:113], v[130:133], v[228:231], v[110:113]
	v_mfma_f32_16x16x32_bf16 v[94:97], v[130:133], v[236:239], v[94:97]
	v_mfma_f32_16x16x32_bf16 v[94:97], v[134:137], v[240:243], v[94:97]
	v_mfma_f32_16x16x32_bf16 v[78:81], v[134:137], v[248:251], v[78:81]
	v_mfma_f32_16x16x32_bf16 v[78:81], v[130:133], v[244:247], v[78:81]
	v_mfma_f32_16x16x32_bf16 v[70:73], v[138:141], v[244:247], v[70:73]
	v_mfma_f32_16x16x32_bf16 v[70:73], v[142:145], v[248:251], v[70:73]
	v_mfma_f32_16x16x32_bf16 v[86:89], v[142:145], v[240:243], v[86:89]
	v_mfma_f32_16x16x32_bf16 v[86:89], v[138:141], v[236:239], v[86:89]
	v_mfma_f32_16x16x32_bf16 v[102:105], v[138:141], v[228:231], v[102:105]
	v_mfma_f32_16x16x32_bf16 v[102:105], v[142:145], v[232:235], v[102:105]
	v_mfma_f32_16x16x32_bf16 v[118:121], v[142:145], v[224:227], v[118:121]
	v_mfma_f32_16x16x32_bf16 v[118:121], v[138:141], v[220:223], v[118:121]
	v_mfma_f32_16x16x32_bf16 v[126:129], v[146:149], v[220:223], v[126:129]
	v_mfma_f32_16x16x32_bf16 v[126:129], v[150:153], v[224:227], v[126:129]
	v_mfma_f32_16x16x32_bf16 v[106:109], v[150:153], v[232:235], v[106:109]
	v_mfma_f32_16x16x32_bf16 v[106:109], v[146:149], v[228:231], v[106:109]
	v_mfma_f32_16x16x32_bf16 v[90:93], v[146:149], v[236:239], v[90:93]
	v_mfma_f32_16x16x32_bf16 v[90:93], v[150:153], v[240:243], v[90:93]
	v_mfma_f32_16x16x32_bf16 v[74:77], v[150:153], v[248:251], v[74:77]
	v_mfma_f32_16x16x32_bf16 v[74:77], v[146:149], v[244:247], v[74:77]
	v_mfma_f32_16x16x32_bf16 v[66:69], v[178:181], v[244:247], v[66:69]
	v_mfma_f32_16x16x32_bf16 v[66:69], v[182:185], v[248:251], v[66:69]
	v_mfma_f32_16x16x32_bf16 v[82:85], v[182:185], v[240:243], v[82:85]
	v_mfma_f32_16x16x32_bf16 v[82:85], v[178:181], v[236:239], v[82:85]
	v_mfma_f32_16x16x32_bf16 v[98:101], v[178:181], v[228:231], v[98:101]
	v_mfma_f32_16x16x32_bf16 v[98:101], v[182:185], v[232:235], v[98:101]
	v_mfma_f32_16x16x32_bf16 v[122:125], v[182:185], v[224:227], v[122:125]
	v_mfma_f32_16x16x32_bf16 v[122:125], v[178:181], v[220:223], v[122:125]
	s_barrier
	s_add_i32 s69, s64, s49
	v_lshl_add_u64 v[252:253], s[44:45], 0, v[156:157]
	s_mov_b32 m0, s69
	ds_read_b128 v[220:223], v215 offset:16384
	ds_read_b128 v[224:227], v215 offset:17408
	ds_read_b128 v[228:231], v215 offset:18432
	ds_read_b128 v[232:235], v215 offset:19456
	ds_read_b128 v[236:239], v215 offset:20480
	ds_read_b128 v[240:243], v215 offset:21504
	ds_read_b128 v[244:247], v215 offset:22528
	ds_read_b128 v[248:251], v215 offset:23552
	global_load_lds_dwordx4 v[252:253], off
	s_add_i32 m0, s69, 0x2000
	s_add_u32 s70, s44, 0xb0000
	v_lshl_add_u64 v[172:173], s[44:45], 0, v[160:161]
	s_addc_u32 s71, s45, 0
	s_add_i32 s69, s65, s49
	global_load_lds_dwordx4 v[172:173], off
	v_lshl_add_u64 v[0:1], s[70:71], 0, v[156:157]
	s_mov_b32 m0, s69
	s_nop 0
	global_load_lds_dwordx4 v[0:1], off
	v_lshl_add_u64 v[0:1], s[70:71], 0, v[160:161]
	s_add_i32 m0, s69, 0x2000
	s_nop 0
	global_load_lds_dwordx4 v[0:1], off
	v_lshl_add_u64 v[0:1], s[46:47], 0, v[154:155]
	s_mov_b32 m0, s51
	s_nop 0
	global_load_lds_dwordx4 v[0:1], off
	v_lshl_add_u64 v[0:1], s[46:47], 0, v[158:159]
	s_mov_b32 m0, s52
	s_nop 0
	global_load_lds_dwordx4 v[0:1], off
	s_waitcnt vmcnt(8)
	s_waitcnt lgkmcnt(0)
	s_barrier
	v_mfma_f32_16x16x32_bf16 v[50:53], v[130:133], v[220:223], v[50:53]
	v_mfma_f32_16x16x32_bf16 v[50:53], v[134:137], v[224:227], v[50:53]
	v_mfma_f32_16x16x32_bf16 v[54:57], v[142:145], v[224:227], v[54:57]
	v_mfma_f32_16x16x32_bf16 v[54:57], v[138:141], v[220:223], v[54:57]
	v_mfma_f32_16x16x32_bf16 v[46:49], v[130:133], v[228:231], v[46:49]
	v_mfma_f32_16x16x32_bf16 v[46:49], v[134:137], v[232:235], v[46:49]
	v_mfma_f32_16x16x32_bf16 v[38:41], v[142:145], v[232:235], v[38:41]
	v_mfma_f32_16x16x32_bf16 v[38:41], v[138:141], v[228:231], v[38:41]
	v_mfma_f32_16x16x32_bf16 v[30:33], v[130:133], v[236:239], v[30:33]
	v_mfma_f32_16x16x32_bf16 v[30:33], v[134:137], v[240:243], v[30:33]
	v_mfma_f32_16x16x32_bf16 v[22:25], v[142:145], v[240:243], v[22:25]
	v_mfma_f32_16x16x32_bf16 v[22:25], v[138:141], v[236:239], v[22:25]
	v_mfma_f32_16x16x32_bf16 v[14:17], v[130:133], v[244:247], v[14:17]
	v_mfma_f32_16x16x32_bf16 v[14:17], v[134:137], v[248:251], v[14:17]
	v_mfma_f32_16x16x32_bf16 v[62:65], v[150:153], v[224:227], v[62:65]
	v_mfma_f32_16x16x32_bf16 v[62:65], v[146:149], v[220:223], v[62:65]
	v_mfma_f32_16x16x32_bf16 v[58:61], v[178:181], v[220:223], v[58:61]
	v_mfma_f32_16x16x32_bf16 v[58:61], v[182:185], v[224:227], v[58:61]
	v_mfma_f32_16x16x32_bf16 v[42:45], v[150:153], v[232:235], v[42:45]
	v_mfma_f32_16x16x32_bf16 v[42:45], v[146:149], v[228:231], v[42:45]
	v_mfma_f32_16x16x32_bf16 v[34:37], v[178:181], v[228:231], v[34:37]
	v_mfma_f32_16x16x32_bf16 v[34:37], v[182:185], v[232:235], v[34:37]
	v_mfma_f32_16x16x32_bf16 v[26:29], v[150:153], v[240:243], v[26:29]
	v_mfma_f32_16x16x32_bf16 v[26:29], v[146:149], v[236:239], v[26:29]
	v_mfma_f32_16x16x32_bf16 v[18:21], v[178:181], v[236:239], v[18:21]
	v_mfma_f32_16x16x32_bf16 v[18:21], v[182:185], v[240:243], v[18:21]
	v_mfma_f32_16x16x32_bf16 v[10:13], v[150:153], v[248:251], v[10:13]
	v_mfma_f32_16x16x32_bf16 v[10:13], v[146:149], v[244:247], v[10:13]
	v_mfma_f32_16x16x32_bf16 v[6:9], v[138:141], v[244:247], v[6:9]
	v_mfma_f32_16x16x32_bf16 v[6:9], v[142:145], v[248:251], v[6:9]
	v_mfma_f32_16x16x32_bf16 v[0:3], v[178:181], v[244:247], v[2:5]
	v_mfma_f32_16x16x32_bf16 v[0:3], v[182:185], v[248:251], v[0:3]
	s_barrier
	s_add_i32 s69, 0, 0x18000
	v_add_u32_e32 v4, s69, v187
	s_add_i32 s70, 0, 0x1c000
	ds_read_b128 v[130:133], v4
	ds_read_b128 v[134:137], v4 offset:1024
	ds_read_b128 v[138:141], v4 offset:2048
	ds_read_b128 v[142:145], v4 offset:3072
	v_add_u32_e32 v4, s70, v187
	ds_read_b128 v[146:149], v4
	ds_read_b128 v[150:153], v4 offset:1024
	ds_read_b128 v[178:181], v4 offset:2048
	ds_read_b128 v[182:185], v4 offset:3072
	s_add_u32 s46, s46, 0x4000
	s_addc_u32 s47, s47, 0
	s_mov_b32 m0, s53
	v_lshl_add_u64 v[4:5], s[46:47], 0, v[154:155]
	ds_read_b128 v[220:223], v215 offset:32768
	ds_read_b128 v[224:227], v215 offset:33792
	ds_read_b128 v[228:231], v215 offset:34816
	ds_read_b128 v[232:235], v215 offset:35840
	ds_read_b128 v[236:239], v215 offset:36864
	ds_read_b128 v[240:243], v215 offset:37888
	ds_read_b128 v[244:247], v215 offset:38912
	ds_read_b128 v[248:251], v215 offset:39936
	global_load_lds_dwordx4 v[4:5], off
	v_lshl_add_u64 v[4:5], s[46:47], 0, v[158:159]
	s_mov_b32 m0, s54
	s_nop 0
	global_load_lds_dwordx4 v[4:5], off
	s_waitcnt vmcnt(8)
	s_waitcnt lgkmcnt(0)
	s_barrier
	v_mfma_f32_16x16x32_bf16 v[114:117], v[130:133], v[220:223], v[114:117]
	v_mfma_f32_16x16x32_bf16 v[114:117], v[134:137], v[224:227], v[114:117]
	v_mfma_f32_16x16x32_bf16 v[110:113], v[134:137], v[232:235], v[110:113]
	v_mfma_f32_16x16x32_bf16 v[110:113], v[130:133], v[228:231], v[110:113]
	v_mfma_f32_16x16x32_bf16 v[94:97], v[130:133], v[236:239], v[94:97]
	v_mfma_f32_16x16x32_bf16 v[94:97], v[134:137], v[240:243], v[94:97]
	v_mfma_f32_16x16x32_bf16 v[78:81], v[134:137], v[248:251], v[78:81]
	v_mfma_f32_16x16x32_bf16 v[78:81], v[130:133], v[244:247], v[78:81]
	v_mfma_f32_16x16x32_bf16 v[70:73], v[138:141], v[244:247], v[70:73]
	v_mfma_f32_16x16x32_bf16 v[70:73], v[142:145], v[248:251], v[70:73]
	v_mfma_f32_16x16x32_bf16 v[86:89], v[142:145], v[240:243], v[86:89]
	v_mfma_f32_16x16x32_bf16 v[86:89], v[138:141], v[236:239], v[86:89]
	v_mfma_f32_16x16x32_bf16 v[102:105], v[138:141], v[228:231], v[102:105]
	v_mfma_f32_16x16x32_bf16 v[102:105], v[142:145], v[232:235], v[102:105]
	v_mfma_f32_16x16x32_bf16 v[118:121], v[142:145], v[224:227], v[118:121]
	v_mfma_f32_16x16x32_bf16 v[118:121], v[138:141], v[220:223], v[118:121]
	v_mfma_f32_16x16x32_bf16 v[126:129], v[146:149], v[220:223], v[126:129]
	v_mfma_f32_16x16x32_bf16 v[126:129], v[150:153], v[224:227], v[126:129]
	v_mfma_f32_16x16x32_bf16 v[106:109], v[150:153], v[232:235], v[106:109]
	v_mfma_f32_16x16x32_bf16 v[106:109], v[146:149], v[228:231], v[106:109]
	v_mfma_f32_16x16x32_bf16 v[90:93], v[146:149], v[236:239], v[90:93]
	v_mfma_f32_16x16x32_bf16 v[90:93], v[150:153], v[240:243], v[90:93]
	v_mfma_f32_16x16x32_bf16 v[74:77], v[150:153], v[248:251], v[74:77]
	v_mfma_f32_16x16x32_bf16 v[74:77], v[146:149], v[244:247], v[74:77]
	v_mfma_f32_16x16x32_bf16 v[66:69], v[178:181], v[244:247], v[66:69]
	v_mfma_f32_16x16x32_bf16 v[66:69], v[182:185], v[248:251], v[66:69]
	v_mfma_f32_16x16x32_bf16 v[82:85], v[182:185], v[240:243], v[82:85]
	v_mfma_f32_16x16x32_bf16 v[82:85], v[178:181], v[236:239], v[82:85]
	v_mfma_f32_16x16x32_bf16 v[98:101], v[178:181], v[228:231], v[98:101]
	v_mfma_f32_16x16x32_bf16 v[98:101], v[182:185], v[232:235], v[98:101]
	v_mfma_f32_16x16x32_bf16 v[122:125], v[182:185], v[224:227], v[122:125]
	v_mfma_f32_16x16x32_bf16 v[122:125], v[178:181], v[220:223], v[122:125]
	s_barrier
	s_add_i32 s46, s69, s49
	v_lshl_add_u64 v[4:5], v[252:253], 0, s[18:19]
	s_mov_b32 m0, s46
	ds_read_b128 v[220:223], v215 offset:49152
	ds_read_b128 v[224:227], v215 offset:50176
	ds_read_b128 v[228:231], v215 offset:51200
	ds_read_b128 v[232:235], v215 offset:52224
	ds_read_b128 v[236:239], v215 offset:53248
	ds_read_b128 v[240:243], v215 offset:54272
	ds_read_b128 v[244:247], v215 offset:55296
	ds_read_b128 v[248:251], v215 offset:56320
	global_load_lds_dwordx4 v[4:5], off
	s_add_i32 m0, s46, 0x2000
	s_add_u32 s44, s44, 0xb0080
	v_lshl_add_u64 v[4:5], v[172:173], 0, s[18:19]
	s_addc_u32 s45, s45, 0
	s_add_i32 s46, s70, s49
	global_load_lds_dwordx4 v[4:5], off
	v_lshl_add_u64 v[4:5], s[44:45], 0, v[156:157]
	s_mov_b32 m0, s46
	s_nop 0
	global_load_lds_dwordx4 v[4:5], off
	v_lshl_add_u64 v[4:5], s[44:45], 0, v[160:161]
	s_add_i32 m0, s46, 0x2000
	s_nop 0
	global_load_lds_dwordx4 v[4:5], off
	v_lshl_add_u64 v[4:5], s[42:43], 0, v[154:155]
	s_mov_b32 m0, s59
	s_nop 0
	global_load_lds_dwordx4 v[4:5], off
	v_lshl_add_u64 v[4:5], s[42:43], 0, v[158:159]
	s_mov_b32 m0, s60
	s_nop 0
	global_load_lds_dwordx4 v[4:5], off
	s_waitcnt vmcnt(8)
	s_waitcnt lgkmcnt(0)
	s_barrier
	v_mfma_f32_16x16x32_bf16 v[50:53], v[130:133], v[220:223], v[50:53]
	v_mfma_f32_16x16x32_bf16 v[50:53], v[134:137], v[224:227], v[50:53]
	v_mfma_f32_16x16x32_bf16 v[54:57], v[142:145], v[224:227], v[54:57]
	v_mfma_f32_16x16x32_bf16 v[54:57], v[138:141], v[220:223], v[54:57]
	v_mfma_f32_16x16x32_bf16 v[46:49], v[130:133], v[228:231], v[46:49]
	v_mfma_f32_16x16x32_bf16 v[46:49], v[134:137], v[232:235], v[46:49]
	v_mfma_f32_16x16x32_bf16 v[38:41], v[142:145], v[232:235], v[38:41]
	v_mfma_f32_16x16x32_bf16 v[38:41], v[138:141], v[228:231], v[38:41]
	v_mfma_f32_16x16x32_bf16 v[30:33], v[130:133], v[236:239], v[30:33]
	v_mfma_f32_16x16x32_bf16 v[30:33], v[134:137], v[240:243], v[30:33]
	v_mfma_f32_16x16x32_bf16 v[22:25], v[142:145], v[240:243], v[22:25]
	v_mfma_f32_16x16x32_bf16 v[22:25], v[138:141], v[236:239], v[22:25]
	v_mfma_f32_16x16x32_bf16 v[14:17], v[130:133], v[244:247], v[14:17]
	v_mfma_f32_16x16x32_bf16 v[14:17], v[134:137], v[248:251], v[14:17]
	v_mfma_f32_16x16x32_bf16 v[62:65], v[150:153], v[224:227], v[62:65]
	v_mfma_f32_16x16x32_bf16 v[62:65], v[146:149], v[220:223], v[62:65]
	v_mfma_f32_16x16x32_bf16 v[58:61], v[178:181], v[220:223], v[58:61]
	v_mfma_f32_16x16x32_bf16 v[58:61], v[182:185], v[224:227], v[58:61]
	v_mfma_f32_16x16x32_bf16 v[42:45], v[150:153], v[232:235], v[42:45]
	v_mfma_f32_16x16x32_bf16 v[42:45], v[146:149], v[228:231], v[42:45]
	v_mfma_f32_16x16x32_bf16 v[34:37], v[178:181], v[228:231], v[34:37]
	v_mfma_f32_16x16x32_bf16 v[34:37], v[182:185], v[232:235], v[34:37]
	v_mfma_f32_16x16x32_bf16 v[26:29], v[150:153], v[240:243], v[26:29]
	v_mfma_f32_16x16x32_bf16 v[26:29], v[146:149], v[236:239], v[26:29]
	v_mfma_f32_16x16x32_bf16 v[18:21], v[178:181], v[236:239], v[18:21]
	v_mfma_f32_16x16x32_bf16 v[18:21], v[182:185], v[240:243], v[18:21]
	v_mfma_f32_16x16x32_bf16 v[10:13], v[150:153], v[248:251], v[10:13]
	v_mfma_f32_16x16x32_bf16 v[10:13], v[146:149], v[244:247], v[10:13]
	v_mfma_f32_16x16x32_bf16 v[4:7], v[138:141], v[244:247], v[6:9]
	v_mfma_f32_16x16x32_bf16 v[6:9], v[142:145], v[248:251], v[4:7]
	v_mfma_f32_16x16x32_bf16 v[0:3], v[178:181], v[244:247], v[0:3]
	v_mfma_f32_16x16x32_bf16 v[2:5], v[182:185], v[248:251], v[0:3]
	s_barrier
	s_add_u32 s11, s11, 0x100
	s_addc_u32 s27, s27, 0
	s_add_u32 s36, s36, 0x800000
	s_addc_u32 s37, s37, 0
	s_cmp_ge_i32 s35, s58
	s_mov_b32 s42, s35
	s_cbranch_scc0 .LBB0_1009
	v_mov_b64_e32 v[234:235], v[174:175]
	s_and_b64 vcc, exec, s[22:23]
	s_cbranch_vccnz .LBB0_980
	s_branch .LBB0_981
